# P3 out-proj epilogue: four residual loads per chunk issued together (halves load round trips); on top of v29
# speedup vs baseline: 1.0003x; 1.0003x over previous
.LBB0_498:
	s_lshl_b32 s27, s52, 8
	s_or_b32 s27, s27, s48
	v_or_b32_e32 v164, s27, v170
	v_ashrrev_i32_e32 v165, 31, v164
	v_lshl_add_u64 v[70:71], v[164:165], 2, s[8:9]
	global_load_dwordx4 v[74:77], v[70:71], off offset:16
	global_load_dwordx4 v[78:81], v[70:71], off
	global_load_dwordx4 v[58:61], v[70:71], off offset:528
	s_nop 0
	global_load_dwordx4 v[70:73], v[70:71], off offset:512
	s_lshl_b32 s29, s38, 8
	s_add_i32 s29, s29, s47
	v_or_b32_e32 v166, s29, v1
	v_cmp_lt_i32_e32 vcc, s63, v166
	s_and_saveexec_b64 s[38:39], vcc
	s_xor_b64 s[38:39], exec, s[38:39]
	v_add_u32_e32 v154, 0xffffe000, v166
	v_lshlrev_b64 v[168:169], 14, v[154:155]
	v_lshl_add_u64 v[168:169], s[12:13], 0, v[168:169]
	v_mov_b32_e32 v167, v155
	s_andn2_saveexec_b64 s[38:39], s[38:39]
	v_ashrrev_i32_e32 v167, 31, v166
	v_lshlrev_b64 v[168:169], 14, v[166:167]
	v_lshl_add_u64 v[168:169], s[10:11], 0, v[168:169]
	s_or_b64 exec, exec, s[38:39]
	v_lshl_add_u64 v[196:197], v[164:165], 2, v[168:169]
	global_load_dwordx4 v[188:191], v[196:197], off
	global_load_dwordx4 v[192:195], v[196:197], off offset:16
	global_load_dwordx4 v[204:207], v[196:197], off offset:512
	global_load_dwordx4 v[208:211], v[196:197], off offset:528
	s_ashr_i32 s29, s29, 2
	s_ashr_i32 s27, s27, 6
	s_and_b32 s52, s29, 0xffffffc0
	s_add_i32 s38, s52, s27
	v_lshlrev_b64 v[198:199], 13, v[166:167]
	s_ashr_i32 s39, s38, 31
	v_and_b32_e32 v168, 56, v164
	v_lshlrev_b32_e32 v154, 6, v166
	v_lshl_add_u64 v[198:199], s[16:17], 0, v[198:199]
	s_lshl_b64 s[38:39], s[38:39], 15
	v_and_or_b32 v154, v154, s64, v168
	v_lshl_add_u64 v[198:199], v[164:165], 1, v[198:199]
	s_add_u32 s38, s18, s38
	v_lshlrev_b32_e32 v154, 1, v154
	s_addc_u32 s39, s19, s39
	v_xor_b32_e32 v169, 32, v187
	s_or_b32 s29, s27, 2
	s_add_i32 s52, s52, s29
	s_ashr_i32 s53, s52, 31
	s_lshl_b64 s[52:53], s[52:53], 15
	s_add_u32 s52, s18, s52
	s_addc_u32 s53, s19, s53
	s_waitcnt vmcnt(2)
	v_pk_add_f32 v[144:145], v[144:145], v[190:191]
	v_pk_add_f32 v[200:201], v[142:143], v[188:189]
	v_pk_add_f32 v[194:195], v[140:141], v[194:195]
	v_pk_add_f32 v[192:193], v[138:139], v[192:193]
	v_cvt_pk_bf16_f32 v138, v200, v201
	v_cvt_pk_bf16_f32 v139, v144, v145
	v_cvt_pk_bf16_f32 v140, v192, v193
	v_cvt_pk_bf16_f32 v141, v194, v195
	v_pk_mul_f32 v[142:143], v[80:81], v[144:145]
	v_pk_mul_f32 v[188:189], v[78:79], v[200:201]
	v_pk_mul_f32 v[190:191], v[76:77], v[194:195]
	v_pk_mul_f32 v[202:203], v[74:75], v[192:193]
	global_store_dwordx4 v[198:199], v[138:141], off
	v_mul_f32_e32 v145, v145, v145
	v_mul_f32_e32 v193, v193, v193
	v_cvt_pk_bf16_f32 v138, v188, v189
	v_cvt_pk_bf16_f32 v139, v142, v143
	v_cvt_pk_bf16_f32 v140, v202, v203
	v_cvt_pk_bf16_f32 v141, v190, v191
	global_store_dwordx4 v154, v[138:141], s[38:39]
	s_nop 0
	s_nop 0
	s_nop 0
	v_and_b32_e32 v139, 64, v187
	v_xor_b32_e32 v138, 16, v187
	v_add_u32_e32 v139, 64, v139
	v_cmp_lt_i32_e32 vcc, v138, v139
	v_mul_f32_e32 v195, v195, v195
	v_fmac_f32_e32 v145, v144, v144
	v_cndmask_b32_e32 v138, v187, v138, vcc
	v_cmp_lt_i32_e32 vcc, v169, v139
	v_lshlrev_b32_e32 v139, 2, v138
	v_fmac_f32_e32 v193, v192, v192
	v_cndmask_b32_e32 v169, v187, v169, vcc
	v_lshlrev_b32_e32 v138, 2, v169
	v_mul_f32_e32 v169, v201, v201
	v_fmac_f32_e32 v169, v200, v200
	v_fmac_f32_e32 v195, v194, v194
	v_add_f32_e32 v144, v169, v145
	v_add_f32_e32 v145, v193, v195
	v_add_f32_e32 v169, v144, v145
	s_waitcnt vmcnt(3)
	v_pk_add_f32 v[136:137], v[136:137], v[206:207]
	v_pk_add_f32 v[134:135], v[134:135], v[204:205]
	s_waitcnt vmcnt(2)
	v_pk_add_f32 v[140:141], v[132:133], v[210:211]
	v_pk_add_f32 v[142:143], v[130:131], v[208:209]
	v_mul_f32_e32 v194, v135, v135
	v_mul_f32_e32 v195, v137, v137
	v_mul_f32_e32 v196, v143, v143
	v_mul_f32_e32 v197, v141, v141
	v_cvt_pk_bf16_f32 v130, v134, v135
	v_cvt_pk_bf16_f32 v131, v136, v137
	v_cvt_pk_bf16_f32 v132, v142, v143
	v_cvt_pk_bf16_f32 v133, v140, v141
	v_fmac_f32_e32 v194, v134, v134
	v_fmac_f32_e32 v195, v136, v136
	v_fmac_f32_e32 v196, v142, v142
	v_fmac_f32_e32 v197, v140, v140
	global_store_dwordx4 v[198:199], v[130:133], off offset:256
	v_pk_mul_f32 v[144:145], v[72:73], v[136:137]
	v_pk_mul_f32 v[188:189], v[70:71], v[134:135]
	v_add_f32_e32 v130, v194, v195
	v_add_f32_e32 v131, v196, v197
	v_add_f32_e32 v130, v130, v131
	v_add_f32_e32 v130, v169, v130
	ds_bpermute_b32 v131, v139, v130
	v_pk_mul_f32 v[190:191], v[60:61], v[140:141]
	v_pk_mul_f32 v[192:193], v[58:59], v[142:143]
	v_cvt_pk_bf16_f32 v132, v188, v189
	v_cvt_pk_bf16_f32 v133, v144, v145
	s_waitcnt lgkmcnt(0)
	v_add_f32_e32 v130, v130, v131
	ds_bpermute_b32 v131, v138, v130
	v_cvt_pk_bf16_f32 v134, v192, v193
	v_cvt_pk_bf16_f32 v135, v190, v191
	global_store_dwordx4 v154, v[132:135], s[52:53]
	s_and_saveexec_b64 s[54:55], s[4:5]
	s_cbranch_execz .LBB0_504
	v_lshl_add_u64 v[132:133], v[166:167], 2, s[20:21]
	s_waitcnt lgkmcnt(0)
	v_add_f32_e32 v130, v130, v131
	global_atomic_add_f32 v[132:133], v130, off
.LBB0_504:
	s_or_b64 exec, exec, s[54:55]
	s_waitcnt lgkmcnt(0)
	v_or_b32_e32 v130, 16, v166
	v_cmp_lt_i32_e32 vcc, s63, v130
	s_and_saveexec_b64 s[54:55], vcc
	s_xor_b64 s[54:55], exec, s[54:55]
	v_add_u32_e32 v154, 0xffffe010, v166
	v_lshlrev_b64 v[132:133], 14, v[154:155]
	v_lshl_add_u64 v[132:133], s[12:13], 0, v[132:133]
	v_mov_b32_e32 v131, v155
	s_andn2_saveexec_b64 s[54:55], s[54:55]
	v_ashrrev_i32_e32 v131, 31, v130
	v_lshlrev_b64 v[132:133], 14, v[130:131]
	v_lshl_add_u64 v[132:133], s[10:11], 0, v[132:133]
	s_or_b64 exec, exec, s[54:55]
	v_lshl_add_u64 v[136:137], v[164:165], 2, v[132:133]
	global_load_dwordx4 v[132:135], v[136:137], off
	global_load_dwordx4 v[140:143], v[136:137], off offset:16
	global_load_dwordx4 v[204:207], v[136:137], off offset:512
	global_load_dwordx4 v[208:211], v[136:137], off offset:528
	v_lshlrev_b64 v[144:145], 13, v[130:131]
	v_lshlrev_b32_e32 v154, 6, v130
	v_lshl_add_u64 v[144:145], s[16:17], 0, v[144:145]
	v_and_or_b32 v154, v154, s65, v168
	v_lshl_add_u64 v[144:145], v[164:165], 1, v[144:145]
	v_lshlrev_b32_e32 v154, 1, v154
	s_waitcnt vmcnt(3)
	v_pk_add_f32 v[134:135], v[128:129], v[134:135]
	v_pk_add_f32 v[132:133], v[126:127], v[132:133]
	s_waitcnt vmcnt(2)
	v_pk_add_f32 v[142:143], v[124:125], v[142:143]
	v_pk_add_f32 v[140:141], v[122:123], v[140:141]
	v_cvt_pk_bf16_f32 v122, v132, v133
	v_cvt_pk_bf16_f32 v123, v134, v135
	v_cvt_pk_bf16_f32 v124, v140, v141
	v_cvt_pk_bf16_f32 v125, v142, v143
	v_pk_mul_f32 v[126:127], v[80:81], v[134:135]
	v_pk_mul_f32 v[128:129], v[78:79], v[132:133]
	v_pk_mul_f32 v[188:189], v[76:77], v[142:143]
	v_pk_mul_f32 v[190:191], v[74:75], v[140:141]
	global_store_dwordx4 v[144:145], v[122:125], off
	v_mul_f32_e32 v133, v133, v133
	v_mul_f32_e32 v135, v135, v135
	v_cvt_pk_bf16_f32 v122, v128, v129
	v_cvt_pk_bf16_f32 v123, v126, v127
	v_cvt_pk_bf16_f32 v124, v190, v191
	v_cvt_pk_bf16_f32 v125, v188, v189
	global_store_dwordx4 v154, v[122:125], s[38:39]
	s_nop 0
	s_nop 0
	s_nop 0
	v_mul_f32_e32 v136, v141, v141
	v_mul_f32_e32 v137, v143, v143
	v_fmac_f32_e32 v133, v132, v132
	v_fmac_f32_e32 v135, v134, v134
	v_fmac_f32_e32 v136, v140, v140
	v_fmac_f32_e32 v137, v142, v142
	v_add_f32_e32 v132, v133, v135
	v_add_f32_e32 v133, v136, v137
	v_add_f32_e32 v132, v132, v133
	s_waitcnt vmcnt(3)
	v_pk_add_f32 v[120:121], v[120:121], v[206:207]
	v_pk_add_f32 v[118:119], v[118:119], v[204:205]
	s_waitcnt vmcnt(2)
	v_pk_add_f32 v[122:123], v[116:117], v[210:211]
	v_pk_add_f32 v[124:125], v[114:115], v[208:209]
	v_mul_f32_e32 v126, v119, v119
	v_mul_f32_e32 v127, v121, v121
	v_mul_f32_e32 v128, v125, v125
	v_mul_f32_e32 v129, v123, v123
	v_cvt_pk_bf16_f32 v114, v118, v119
	v_cvt_pk_bf16_f32 v115, v120, v121
	v_cvt_pk_bf16_f32 v116, v124, v125
	v_cvt_pk_bf16_f32 v117, v122, v123
	v_fmac_f32_e32 v126, v118, v118
	v_fmac_f32_e32 v127, v120, v120
	v_fmac_f32_e32 v128, v124, v124
	v_fmac_f32_e32 v129, v122, v122
	global_store_dwordx4 v[144:145], v[114:117], off offset:256
	v_pk_mul_f32 v[120:121], v[72:73], v[120:121]
	v_pk_mul_f32 v[122:123], v[60:61], v[122:123]
	v_add_f32_e32 v114, v126, v127
	v_add_f32_e32 v115, v128, v129
	v_add_f32_e32 v114, v114, v115
	v_add_f32_e32 v117, v132, v114
	ds_bpermute_b32 v126, v139, v117
	v_pk_mul_f32 v[114:115], v[70:71], v[118:119]
	v_pk_mul_f32 v[118:119], v[58:59], v[124:125]
	v_cvt_pk_bf16_f32 v116, v114, v115
	v_cvt_pk_bf16_f32 v118, v118, v119
	s_waitcnt lgkmcnt(0)
	v_add_f32_e32 v114, v117, v126
	ds_bpermute_b32 v115, v138, v114
	v_cvt_pk_bf16_f32 v117, v120, v121
	v_cvt_pk_bf16_f32 v119, v122, v123
	global_store_dwordx4 v154, v[116:119], s[52:53]
	s_and_saveexec_b64 s[54:55], s[4:5]
	s_cbranch_execz .LBB0_510
	v_lshl_add_u64 v[116:117], v[130:131], 2, s[20:21]
	s_waitcnt lgkmcnt(0)
	v_add_f32_e32 v114, v114, v115
	global_atomic_add_f32 v[116:117], v114, off
.LBB0_510:
	s_or_b64 exec, exec, s[54:55]
	s_waitcnt lgkmcnt(0)
	v_or_b32_e32 v114, 32, v166
	v_cmp_lt_i32_e32 vcc, s63, v114
	s_and_saveexec_b64 s[54:55], vcc
	s_xor_b64 s[54:55], exec, s[54:55]
	v_add_u32_e32 v154, 0xffffe020, v166
	v_lshlrev_b64 v[116:117], 14, v[154:155]
	v_lshl_add_u64 v[116:117], s[12:13], 0, v[116:117]
	v_mov_b32_e32 v115, v155
	s_andn2_saveexec_b64 s[54:55], s[54:55]
	v_ashrrev_i32_e32 v115, 31, v114
	v_lshlrev_b64 v[116:117], 14, v[114:115]
	v_lshl_add_u64 v[116:117], s[10:11], 0, v[116:117]
	s_or_b64 exec, exec, s[54:55]
	v_lshl_add_u64 v[124:125], v[164:165], 2, v[116:117]
	global_load_dwordx4 v[116:119], v[124:125], off
	global_load_dwordx4 v[120:123], v[124:125], off offset:16
	global_load_dwordx4 v[204:207], v[124:125], off offset:512
	global_load_dwordx4 v[208:211], v[124:125], off offset:528
	v_lshlrev_b64 v[126:127], 13, v[114:115]
	v_lshlrev_b32_e32 v128, 6, v114
	v_and_or_b32 v128, v128, s66, v168
	v_lshl_add_u64 v[126:127], s[16:17], 0, v[126:127]
	v_lshl_add_u64 v[126:127], v[164:165], 1, v[126:127]
	v_lshlrev_b32_e32 v132, 1, v128
	s_waitcnt vmcnt(3)
	v_pk_add_f32 v[118:119], v[112:113], v[118:119]
	v_pk_add_f32 v[116:117], v[110:111], v[116:117]
	s_waitcnt vmcnt(2)
	v_pk_add_f32 v[122:123], v[108:109], v[122:123]
	v_pk_add_f32 v[120:121], v[106:107], v[120:121]
	v_cvt_pk_bf16_f32 v106, v116, v117
	v_cvt_pk_bf16_f32 v107, v118, v119
	v_cvt_pk_bf16_f32 v108, v120, v121
	v_cvt_pk_bf16_f32 v109, v122, v123
	v_pk_mul_f32 v[110:111], v[80:81], v[118:119]
	v_pk_mul_f32 v[112:113], v[78:79], v[116:117]
	v_pk_mul_f32 v[128:129], v[76:77], v[122:123]
	v_pk_mul_f32 v[130:131], v[74:75], v[120:121]
	global_store_dwordx4 v[126:127], v[106:109], off
	v_mul_f32_e32 v117, v117, v117
	v_mul_f32_e32 v119, v119, v119
	v_cvt_pk_bf16_f32 v106, v112, v113
	v_cvt_pk_bf16_f32 v107, v110, v111
	v_cvt_pk_bf16_f32 v108, v130, v131
	v_cvt_pk_bf16_f32 v109, v128, v129
	global_store_dwordx4 v132, v[106:109], s[38:39]
	s_nop 0
	s_nop 0
	s_nop 0
	v_mul_f32_e32 v121, v121, v121
	v_mul_f32_e32 v123, v123, v123
	v_fmac_f32_e32 v117, v116, v116
	v_fmac_f32_e32 v119, v118, v118
	v_fmac_f32_e32 v121, v120, v120
	v_fmac_f32_e32 v123, v122, v122
	v_add_f32_e32 v116, v117, v119
	v_add_f32_e32 v117, v121, v123
	v_add_f32_e32 v116, v116, v117
	s_waitcnt vmcnt(3)
	v_pk_add_f32 v[104:105], v[104:105], v[206:207]
	v_pk_add_f32 v[102:103], v[102:103], v[204:205]
	s_waitcnt vmcnt(2)
	v_pk_add_f32 v[106:107], v[100:101], v[210:211]
	v_pk_add_f32 v[108:109], v[98:99], v[208:209]
	v_mul_f32_e32 v110, v103, v103
	v_mul_f32_e32 v111, v105, v105
	v_mul_f32_e32 v112, v109, v109
	v_mul_f32_e32 v113, v107, v107
	v_cvt_pk_bf16_f32 v98, v102, v103
	v_cvt_pk_bf16_f32 v99, v104, v105
	v_cvt_pk_bf16_f32 v100, v108, v109
	v_cvt_pk_bf16_f32 v101, v106, v107
	v_fmac_f32_e32 v110, v102, v102
	v_fmac_f32_e32 v111, v104, v104
	v_fmac_f32_e32 v112, v108, v108
	v_fmac_f32_e32 v113, v106, v106
	global_store_dwordx4 v[126:127], v[98:101], off offset:256
	v_pk_mul_f32 v[104:105], v[72:73], v[104:105]
	v_pk_mul_f32 v[106:107], v[60:61], v[106:107]
	v_add_f32_e32 v98, v110, v111
	v_add_f32_e32 v99, v112, v113
	v_add_f32_e32 v98, v98, v99
	v_add_f32_e32 v101, v116, v98
	ds_bpermute_b32 v110, v139, v101
	v_pk_mul_f32 v[98:99], v[70:71], v[102:103]
	v_pk_mul_f32 v[102:103], v[58:59], v[108:109]
	v_cvt_pk_bf16_f32 v100, v98, v99
	v_cvt_pk_bf16_f32 v102, v102, v103
	s_waitcnt lgkmcnt(0)
	v_add_f32_e32 v98, v101, v110
	ds_bpermute_b32 v99, v138, v98
	v_cvt_pk_bf16_f32 v101, v104, v105
	v_cvt_pk_bf16_f32 v103, v106, v107
	global_store_dwordx4 v132, v[100:103], s[52:53]
	s_and_saveexec_b64 s[54:55], s[4:5]
	s_cbranch_execz .LBB0_516
	v_lshl_add_u64 v[100:101], v[114:115], 2, s[20:21]
	s_waitcnt lgkmcnt(0)
	v_add_f32_e32 v98, v98, v99
	global_atomic_add_f32 v[100:101], v98, off
.LBB0_516:
	s_or_b64 exec, exec, s[54:55]
	s_waitcnt lgkmcnt(0)
	v_or_b32_e32 v98, 48, v166
	v_cmp_lt_i32_e32 vcc, s63, v98
	s_and_saveexec_b64 s[54:55], vcc
	s_xor_b64 s[54:55], exec, s[54:55]
	v_add_u32_e32 v154, 0xffffe030, v166
	v_lshlrev_b64 v[100:101], 14, v[154:155]
	v_lshl_add_u64 v[100:101], s[12:13], 0, v[100:101]
	v_mov_b32_e32 v99, v155
	s_andn2_saveexec_b64 s[54:55], s[54:55]
	v_ashrrev_i32_e32 v99, 31, v98
	v_lshlrev_b64 v[100:101], 14, v[98:99]
	v_lshl_add_u64 v[100:101], s[10:11], 0, v[100:101]
	s_or_b64 exec, exec, s[54:55]
	v_lshl_add_u64 v[108:109], v[164:165], 2, v[100:101]
	global_load_dwordx4 v[100:103], v[108:109], off
	global_load_dwordx4 v[104:107], v[108:109], off offset:16
	global_load_dwordx4 v[204:207], v[108:109], off offset:512
	global_load_dwordx4 v[208:211], v[108:109], off offset:528
	v_lshlrev_b64 v[110:111], 13, v[98:99]
	v_lshlrev_b32_e32 v112, 6, v98
	v_and_or_b32 v112, v112, s67, v168
	v_lshl_add_u64 v[110:111], s[16:17], 0, v[110:111]
	v_lshl_add_u64 v[110:111], v[164:165], 1, v[110:111]
	v_lshlrev_b32_e32 v116, 1, v112
	s_waitcnt vmcnt(3)
	v_pk_add_f32 v[102:103], v[96:97], v[102:103]
	v_pk_add_f32 v[100:101], v[94:95], v[100:101]
	s_waitcnt vmcnt(2)
	v_pk_add_f32 v[106:107], v[92:93], v[106:107]
	v_pk_add_f32 v[104:105], v[90:91], v[104:105]
	v_cvt_pk_bf16_f32 v90, v100, v101
	v_cvt_pk_bf16_f32 v91, v102, v103
	v_cvt_pk_bf16_f32 v92, v104, v105
	v_cvt_pk_bf16_f32 v93, v106, v107
	v_pk_mul_f32 v[94:95], v[80:81], v[102:103]
	v_pk_mul_f32 v[96:97], v[78:79], v[100:101]
	v_pk_mul_f32 v[112:113], v[76:77], v[106:107]
	v_pk_mul_f32 v[114:115], v[74:75], v[104:105]
	global_store_dwordx4 v[110:111], v[90:93], off
	v_mul_f32_e32 v101, v101, v101
	v_mul_f32_e32 v103, v103, v103
	v_cvt_pk_bf16_f32 v90, v96, v97
	v_cvt_pk_bf16_f32 v91, v94, v95
	v_cvt_pk_bf16_f32 v92, v114, v115
	v_cvt_pk_bf16_f32 v93, v112, v113
	global_store_dwordx4 v116, v[90:93], s[38:39]
	s_nop 0
	s_nop 0
	s_nop 0
	v_mul_f32_e32 v105, v105, v105
	v_mul_f32_e32 v107, v107, v107
	v_fmac_f32_e32 v101, v100, v100
	v_fmac_f32_e32 v103, v102, v102
	v_fmac_f32_e32 v105, v104, v104
	v_fmac_f32_e32 v107, v106, v106
	v_add_f32_e32 v100, v101, v103
	v_add_f32_e32 v101, v105, v107
	v_add_f32_e32 v100, v100, v101
	s_waitcnt vmcnt(3)
	v_pk_add_f32 v[88:89], v[88:89], v[206:207]
	v_pk_add_f32 v[86:87], v[86:87], v[204:205]
	s_waitcnt vmcnt(2)
	v_pk_add_f32 v[90:91], v[84:85], v[210:211]
	v_pk_add_f32 v[92:93], v[82:83], v[208:209]
	v_mul_f32_e32 v94, v87, v87
	v_mul_f32_e32 v95, v89, v89
	v_mul_f32_e32 v96, v93, v93
	v_mul_f32_e32 v97, v91, v91
	v_cvt_pk_bf16_f32 v82, v86, v87
	v_cvt_pk_bf16_f32 v83, v88, v89
	v_cvt_pk_bf16_f32 v84, v92, v93
	v_cvt_pk_bf16_f32 v85, v90, v91
	v_fmac_f32_e32 v94, v86, v86
	v_fmac_f32_e32 v95, v88, v88
	v_fmac_f32_e32 v96, v92, v92
	v_fmac_f32_e32 v97, v90, v90
	global_store_dwordx4 v[110:111], v[82:85], off offset:256
	v_pk_mul_f32 v[88:89], v[72:73], v[88:89]
	v_pk_mul_f32 v[90:91], v[60:61], v[90:91]
	v_add_f32_e32 v82, v94, v95
	v_add_f32_e32 v83, v96, v97
	v_add_f32_e32 v82, v82, v83
	v_add_f32_e32 v85, v100, v82
	ds_bpermute_b32 v94, v139, v85
	v_pk_mul_f32 v[82:83], v[70:71], v[86:87]
	v_pk_mul_f32 v[86:87], v[58:59], v[92:93]
	v_cvt_pk_bf16_f32 v84, v82, v83
	v_cvt_pk_bf16_f32 v86, v86, v87
	s_waitcnt lgkmcnt(0)
	v_add_f32_e32 v82, v85, v94
	ds_bpermute_b32 v83, v138, v82
	v_cvt_pk_bf16_f32 v85, v88, v89
	v_cvt_pk_bf16_f32 v87, v90, v91
	global_store_dwordx4 v116, v[84:87], s[52:53]
	s_and_saveexec_b64 s[38:39], s[4:5]
	s_cbranch_execz .LBB0_522
	v_lshl_add_u64 v[84:85], v[98:99], 2, s[20:21]
	s_waitcnt lgkmcnt(0)
	v_add_f32_e32 v82, v82, v83
	global_atomic_add_f32 v[84:85], v82, off

.LBB0_526:
	s_or_b64 exec, exec, s[38:39]
	s_waitcnt lgkmcnt(0)
	v_lshl_add_u64 v[94:95], v[164:165], 2, v[82:83]
	global_load_dwordx4 v[86:89], v[94:95], off
	global_load_dwordx4 v[90:93], v[94:95], off offset:16
	global_load_dwordx4 v[204:207], v[94:95], off offset:512
	global_load_dwordx4 v[208:211], v[94:95], off offset:528
	v_ashrrev_i32_e32 v96, 2, v84
	v_lshlrev_b64 v[82:83], 13, v[84:85]
	v_lshlrev_b32_e32 v97, 6, v84
	v_and_b32_e32 v104, 0xffffffc0, v96
	v_lshl_add_u64 v[82:83], s[16:17], 0, v[82:83]
	v_and_or_b32 v98, v97, s64, v168
	v_lshl_add_u64 v[96:97], v[164:165], 1, v[82:83]
	v_add_u32_e32 v82, s27, v104
	v_ashrrev_i32_e32 v83, 31, v82
	v_lshlrev_b64 v[82:83], 15, v[82:83]
	v_lshlrev_b32_e32 v154, 1, v98
	v_lshl_add_u64 v[82:83], s[18:19], 0, v[82:83]
	v_lshl_add_u64 v[98:99], v[82:83], 0, v[154:155]
	s_waitcnt vmcnt(3)
	v_pk_add_f32 v[88:89], v[68:69], v[88:89]
	v_pk_add_f32 v[86:87], v[66:67], v[86:87]
	s_waitcnt vmcnt(2)
	v_pk_add_f32 v[92:93], v[64:65], v[92:93]
	v_pk_add_f32 v[90:91], v[62:63], v[90:91]
	v_cvt_pk_bf16_f32 v62, v86, v87
	v_cvt_pk_bf16_f32 v63, v88, v89
	v_cvt_pk_bf16_f32 v64, v90, v91
	v_cvt_pk_bf16_f32 v65, v92, v93
	v_pk_mul_f32 v[66:67], v[80:81], v[88:89]
	v_pk_mul_f32 v[68:69], v[78:79], v[86:87]
	v_pk_mul_f32 v[100:101], v[76:77], v[92:93]
	v_pk_mul_f32 v[102:103], v[74:75], v[90:91]
	global_store_dwordx4 v[96:97], v[62:65], off
	v_mul_f32_e32 v87, v87, v87
	v_mul_f32_e32 v89, v89, v89
	v_cvt_pk_bf16_f32 v62, v68, v69
	v_cvt_pk_bf16_f32 v63, v66, v67
	v_cvt_pk_bf16_f32 v64, v102, v103
	v_cvt_pk_bf16_f32 v65, v100, v101
	global_store_dwordx4 v[98:99], v[62:65], off
	s_nop 0
	s_nop 0
	s_nop 0
	v_mul_f32_e32 v91, v91, v91
	v_mul_f32_e32 v93, v93, v93
	v_fmac_f32_e32 v87, v86, v86
	v_fmac_f32_e32 v89, v88, v88
	v_fmac_f32_e32 v91, v90, v90
	v_fmac_f32_e32 v93, v92, v92
	v_add_f32_e32 v86, v87, v89
	v_add_f32_e32 v87, v91, v93
	v_add_f32_e32 v90, v86, v87
	s_waitcnt vmcnt(3)
	v_pk_add_f32 v[56:57], v[56:57], v[206:207]
	v_pk_add_f32 v[54:55], v[54:55], v[204:205]
	s_waitcnt vmcnt(2)
	v_pk_add_f32 v[62:63], v[52:53], v[210:211]
	v_pk_add_f32 v[64:65], v[50:51], v[208:209]
	v_mul_f32_e32 v91, v55, v55
	v_mul_f32_e32 v92, v57, v57
	v_mul_f32_e32 v93, v65, v65
	v_mul_f32_e32 v94, v63, v63
	v_cvt_pk_bf16_f32 v50, v54, v55
	v_cvt_pk_bf16_f32 v51, v56, v57
	v_cvt_pk_bf16_f32 v52, v64, v65
	v_cvt_pk_bf16_f32 v53, v62, v63
	v_fmac_f32_e32 v91, v54, v54
	v_fmac_f32_e32 v92, v56, v56
	v_fmac_f32_e32 v93, v64, v64
	v_fmac_f32_e32 v94, v62, v62
	global_store_dwordx4 v[96:97], v[50:53], off offset:256
	v_pk_mul_f32 v[66:67], v[72:73], v[56:57]
	v_pk_mul_f32 v[68:69], v[70:71], v[54:55]
	v_add_f32_e32 v50, v91, v92
	v_add_f32_e32 v51, v93, v94
	v_add_f32_e32 v50, v50, v51
	v_add_f32_e32 v52, v90, v50
	ds_bpermute_b32 v53, v139, v52
	v_add_u32_e32 v50, s29, v104
	v_ashrrev_i32_e32 v51, 31, v50
	v_lshlrev_b64 v[50:51], 15, v[50:51]
	v_pk_mul_f32 v[86:87], v[60:61], v[62:63]
	s_waitcnt lgkmcnt(0)
	v_add_f32_e32 v52, v52, v53
	ds_bpermute_b32 v53, v138, v52
	v_pk_mul_f32 v[88:89], v[58:59], v[64:65]
	v_lshl_add_u64 v[50:51], s[18:19], 0, v[50:51]
	v_cvt_pk_bf16_f32 v54, v68, v69
	v_cvt_pk_bf16_f32 v55, v66, v67
	v_cvt_pk_bf16_f32 v56, v88, v89
	v_cvt_pk_bf16_f32 v57, v86, v87
	v_lshl_add_u64 v[62:63], v[50:51], 0, v[154:155]
	global_store_dwordx4 v[62:63], v[54:57], off
	s_and_saveexec_b64 s[38:39], s[4:5]
	s_cbranch_execz .LBB0_528
	v_lshl_add_u64 v[54:55], v[84:85], 2, s[20:21]
	s_waitcnt lgkmcnt(0)
	v_add_f32_e32 v52, v52, v53
	global_atomic_add_f32 v[54:55], v52, off
.LBB0_528:
	s_or_b64 exec, exec, s[38:39]
	s_waitcnt lgkmcnt(0)
	v_add_u32_e32 v52, 0x90, v166
	v_cmp_lt_i32_e32 vcc, s69, v166
	s_and_saveexec_b64 s[38:39], vcc
	s_xor_b64 s[38:39], exec, s[38:39]
	v_add_u32_e32 v154, 0xffffe090, v166
	v_lshlrev_b64 v[54:55], 14, v[154:155]
	v_lshl_add_u64 v[54:55], s[12:13], 0, v[54:55]
	v_mov_b32_e32 v53, v155
	s_andn2_saveexec_b64 s[38:39], s[38:39]
	v_ashrrev_i32_e32 v53, 31, v52
	v_lshlrev_b64 v[54:55], 14, v[52:53]
	v_lshl_add_u64 v[54:55], s[10:11], 0, v[54:55]
	s_or_b64 exec, exec, s[38:39]
	v_lshl_add_u64 v[66:67], v[164:165], 2, v[54:55]
	global_load_dwordx4 v[54:57], v[66:67], off
	global_load_dwordx4 v[62:65], v[66:67], off offset:16
	global_load_dwordx4 v[204:207], v[66:67], off offset:512
	global_load_dwordx4 v[208:211], v[66:67], off offset:528
	v_lshlrev_b64 v[68:69], 13, v[52:53]
	v_lshlrev_b32_e32 v84, 6, v52
	v_and_or_b32 v84, v84, s65, v168
	v_lshl_add_u64 v[68:69], s[16:17], 0, v[68:69]
	v_lshl_add_u64 v[68:69], v[164:165], 1, v[68:69]
	v_lshlrev_b32_e32 v154, 1, v84
	v_lshl_add_u64 v[84:85], v[82:83], 0, v[154:155]
	s_waitcnt vmcnt(3)
	v_pk_add_f32 v[56:57], v[48:49], v[56:57]
	v_pk_add_f32 v[54:55], v[46:47], v[54:55]
	s_waitcnt vmcnt(2)
	v_pk_add_f32 v[64:65], v[44:45], v[64:65]
	v_pk_add_f32 v[62:63], v[42:43], v[62:63]
	v_cvt_pk_bf16_f32 v42, v54, v55
	v_cvt_pk_bf16_f32 v43, v56, v57
	v_cvt_pk_bf16_f32 v44, v62, v63
	v_cvt_pk_bf16_f32 v45, v64, v65
	v_pk_mul_f32 v[46:47], v[80:81], v[56:57]
	v_pk_mul_f32 v[48:49], v[78:79], v[54:55]
	v_pk_mul_f32 v[86:87], v[76:77], v[64:65]
	v_pk_mul_f32 v[88:89], v[74:75], v[62:63]
	global_store_dwordx4 v[68:69], v[42:45], off
	v_mul_f32_e32 v55, v55, v55
	v_mul_f32_e32 v57, v57, v57
	v_cvt_pk_bf16_f32 v42, v48, v49
	v_cvt_pk_bf16_f32 v43, v46, v47
	v_cvt_pk_bf16_f32 v44, v88, v89
	v_cvt_pk_bf16_f32 v45, v86, v87
	global_store_dwordx4 v[84:85], v[42:45], off
	s_nop 0
	s_nop 0
	s_nop 0
	v_mul_f32_e32 v63, v63, v63
	v_mul_f32_e32 v65, v65, v65
	v_fmac_f32_e32 v55, v54, v54
	v_fmac_f32_e32 v57, v56, v56
	v_fmac_f32_e32 v63, v62, v62
	v_fmac_f32_e32 v65, v64, v64
	v_add_f32_e32 v54, v55, v57
	v_add_f32_e32 v55, v63, v65
	v_add_f32_e32 v54, v54, v55
	s_waitcnt vmcnt(3)
	v_pk_add_f32 v[40:41], v[40:41], v[206:207]
	v_pk_add_f32 v[38:39], v[38:39], v[204:205]
	s_waitcnt vmcnt(2)
	v_pk_add_f32 v[42:43], v[36:37], v[210:211]
	v_pk_add_f32 v[44:45], v[34:35], v[208:209]
	v_mul_f32_e32 v48, v39, v39
	v_mul_f32_e32 v49, v41, v41
	v_mul_f32_e32 v55, v45, v45
	v_mul_f32_e32 v56, v43, v43
	v_cvt_pk_bf16_f32 v34, v38, v39
	v_cvt_pk_bf16_f32 v35, v40, v41
	v_cvt_pk_bf16_f32 v36, v44, v45
	v_cvt_pk_bf16_f32 v37, v42, v43
	v_fmac_f32_e32 v48, v38, v38
	v_fmac_f32_e32 v49, v40, v40
	v_fmac_f32_e32 v55, v44, v44
	v_fmac_f32_e32 v56, v42, v42
	global_store_dwordx4 v[68:69], v[34:37], off offset:256
	v_pk_mul_f32 v[46:47], v[72:73], v[40:41]
	v_pk_mul_f32 v[40:41], v[60:61], v[42:43]
	v_add_f32_e32 v34, v48, v49
	v_add_f32_e32 v35, v55, v56
	v_add_f32_e32 v34, v34, v35
	v_add_f32_e32 v48, v54, v34
	ds_bpermute_b32 v49, v139, v48
	v_pk_mul_f32 v[34:35], v[70:71], v[38:39]
	v_pk_mul_f32 v[38:39], v[58:59], v[44:45]
	v_cvt_pk_bf16_f32 v36, v34, v35
	v_cvt_pk_bf16_f32 v37, v46, v47
	s_waitcnt lgkmcnt(0)
	v_add_f32_e32 v34, v48, v49
	ds_bpermute_b32 v35, v138, v34
	v_cvt_pk_bf16_f32 v38, v38, v39
	v_cvt_pk_bf16_f32 v39, v40, v41
	v_lshl_add_u64 v[40:41], v[50:51], 0, v[154:155]
	global_store_dwordx4 v[40:41], v[36:39], off
	s_and_saveexec_b64 s[38:39], s[4:5]
	s_cbranch_execz .LBB0_534
	v_lshl_add_u64 v[36:37], v[52:53], 2, s[20:21]
	s_waitcnt lgkmcnt(0)
	v_add_f32_e32 v34, v34, v35
	global_atomic_add_f32 v[36:37], v34, off
.LBB0_534:
	s_or_b64 exec, exec, s[38:39]
	s_waitcnt lgkmcnt(0)
	v_add_u32_e32 v34, 0xa0, v166
	v_cmp_lt_i32_e32 vcc, s70, v166
	s_and_saveexec_b64 s[38:39], vcc
	s_xor_b64 s[38:39], exec, s[38:39]
	v_add_u32_e32 v154, 0xffffe0a0, v166
	v_lshlrev_b64 v[36:37], 14, v[154:155]
	v_lshl_add_u64 v[36:37], s[12:13], 0, v[36:37]
	v_mov_b32_e32 v35, v155
	s_andn2_saveexec_b64 s[38:39], s[38:39]
	v_ashrrev_i32_e32 v35, 31, v34
	v_lshlrev_b64 v[36:37], 14, v[34:35]
	v_lshl_add_u64 v[36:37], s[10:11], 0, v[36:37]
	s_or_b64 exec, exec, s[38:39]
	v_lshl_add_u64 v[44:45], v[164:165], 2, v[36:37]
	global_load_dwordx4 v[36:39], v[44:45], off
	global_load_dwordx4 v[40:43], v[44:45], off offset:16
	global_load_dwordx4 v[204:207], v[44:45], off offset:512
	global_load_dwordx4 v[208:211], v[44:45], off offset:528
	v_lshlrev_b64 v[46:47], 13, v[34:35]
	v_lshlrev_b32_e32 v48, 6, v34
	v_and_or_b32 v48, v48, s66, v168
	v_lshl_add_u64 v[46:47], s[16:17], 0, v[46:47]
	v_lshl_add_u64 v[46:47], v[164:165], 1, v[46:47]
	v_lshlrev_b32_e32 v154, 1, v48
	v_lshl_add_u64 v[48:49], v[82:83], 0, v[154:155]
	s_waitcnt vmcnt(3)
	v_pk_add_f32 v[38:39], v[32:33], v[38:39]
	v_pk_add_f32 v[36:37], v[30:31], v[36:37]
	s_waitcnt vmcnt(2)
	v_pk_add_f32 v[42:43], v[28:29], v[42:43]
	v_pk_add_f32 v[40:41], v[26:27], v[40:41]
	v_cvt_pk_bf16_f32 v26, v36, v37
	v_cvt_pk_bf16_f32 v27, v38, v39
	v_cvt_pk_bf16_f32 v28, v40, v41
	v_cvt_pk_bf16_f32 v29, v42, v43
	v_pk_mul_f32 v[30:31], v[80:81], v[38:39]
	v_pk_mul_f32 v[32:33], v[78:79], v[36:37]
	v_pk_mul_f32 v[52:53], v[76:77], v[42:43]
	v_pk_mul_f32 v[54:55], v[74:75], v[40:41]
	global_store_dwordx4 v[46:47], v[26:29], off
	v_mul_f32_e32 v37, v37, v37
	v_mul_f32_e32 v39, v39, v39
	v_cvt_pk_bf16_f32 v26, v32, v33
	v_cvt_pk_bf16_f32 v27, v30, v31
	v_cvt_pk_bf16_f32 v28, v54, v55
	v_cvt_pk_bf16_f32 v29, v52, v53
	global_store_dwordx4 v[48:49], v[26:29], off
	s_nop 0
	s_nop 0
	s_nop 0
	v_mul_f32_e32 v41, v41, v41
	v_mul_f32_e32 v43, v43, v43
	v_fmac_f32_e32 v37, v36, v36
	v_fmac_f32_e32 v39, v38, v38
	v_fmac_f32_e32 v41, v40, v40
	v_fmac_f32_e32 v43, v42, v42
	v_add_f32_e32 v36, v37, v39
	v_add_f32_e32 v37, v41, v43
	v_add_f32_e32 v36, v36, v37
	s_waitcnt vmcnt(3)
	v_pk_add_f32 v[24:25], v[24:25], v[206:207]
	v_pk_add_f32 v[22:23], v[22:23], v[204:205]
	s_waitcnt vmcnt(2)
	v_pk_add_f32 v[26:27], v[20:21], v[210:211]
	v_pk_add_f32 v[28:29], v[18:19], v[208:209]
	v_mul_f32_e32 v32, v23, v23
	v_mul_f32_e32 v33, v25, v25
	v_mul_f32_e32 v37, v29, v29
	v_mul_f32_e32 v38, v27, v27
	v_cvt_pk_bf16_f32 v18, v22, v23
	v_cvt_pk_bf16_f32 v19, v24, v25
	v_cvt_pk_bf16_f32 v20, v28, v29
	v_cvt_pk_bf16_f32 v21, v26, v27
	v_fmac_f32_e32 v32, v22, v22
	v_fmac_f32_e32 v33, v24, v24
	v_fmac_f32_e32 v37, v28, v28
	v_fmac_f32_e32 v38, v26, v26
	global_store_dwordx4 v[46:47], v[18:21], off offset:256
	v_pk_mul_f32 v[30:31], v[72:73], v[24:25]
	v_pk_mul_f32 v[24:25], v[60:61], v[26:27]
	v_add_f32_e32 v18, v32, v33
	v_add_f32_e32 v19, v37, v38
	v_add_f32_e32 v18, v18, v19
	v_add_f32_e32 v32, v36, v18
	ds_bpermute_b32 v33, v139, v32
	v_pk_mul_f32 v[18:19], v[70:71], v[22:23]
	v_pk_mul_f32 v[22:23], v[58:59], v[28:29]
	v_cvt_pk_bf16_f32 v20, v18, v19
	v_cvt_pk_bf16_f32 v21, v30, v31
	s_waitcnt lgkmcnt(0)
	v_add_f32_e32 v18, v32, v33
	ds_bpermute_b32 v19, v138, v18
	v_cvt_pk_bf16_f32 v22, v22, v23
	v_cvt_pk_bf16_f32 v23, v24, v25
	v_lshl_add_u64 v[24:25], v[50:51], 0, v[154:155]
	global_store_dwordx4 v[24:25], v[20:23], off
	s_and_saveexec_b64 s[38:39], s[4:5]
	s_cbranch_execz .LBB0_540
	v_lshl_add_u64 v[20:21], v[34:35], 2, s[20:21]
	s_waitcnt lgkmcnt(0)
	v_add_f32_e32 v18, v18, v19
	global_atomic_add_f32 v[20:21], v18, off
.LBB0_540:
	s_or_b64 exec, exec, s[38:39]
	s_waitcnt lgkmcnt(0)
	v_add_u32_e32 v18, 0xb0, v166
	v_cmp_lt_i32_e32 vcc, s71, v166
	s_and_saveexec_b64 s[38:39], vcc
	s_xor_b64 s[38:39], exec, s[38:39]
	v_add_u32_e32 v154, 0xffffe0b0, v166
	v_lshlrev_b64 v[20:21], 14, v[154:155]
	v_lshl_add_u64 v[20:21], s[12:13], 0, v[20:21]
	v_mov_b32_e32 v19, v155
	s_andn2_saveexec_b64 s[38:39], s[38:39]
	v_ashrrev_i32_e32 v19, 31, v18
	v_lshlrev_b64 v[20:21], 14, v[18:19]
	v_lshl_add_u64 v[20:21], s[10:11], 0, v[20:21]
	s_or_b64 exec, exec, s[38:39]
	v_lshl_add_u64 v[28:29], v[164:165], 2, v[20:21]
	global_load_dwordx4 v[20:23], v[28:29], off
	global_load_dwordx4 v[24:27], v[28:29], off offset:16
	global_load_dwordx4 v[204:207], v[28:29], off offset:512
	global_load_dwordx4 v[208:211], v[28:29], off offset:528
	v_lshlrev_b64 v[30:31], 13, v[18:19]
	v_lshlrev_b32_e32 v32, 6, v18
	v_and_or_b32 v32, v32, s67, v168
	v_lshl_add_u64 v[30:31], s[16:17], 0, v[30:31]
	v_lshl_add_u64 v[30:31], v[164:165], 1, v[30:31]
	v_lshlrev_b32_e32 v154, 1, v32
	v_lshl_add_u64 v[32:33], v[82:83], 0, v[154:155]
	s_waitcnt vmcnt(3)
	v_pk_add_f32 v[22:23], v[16:17], v[22:23]
	v_pk_add_f32 v[20:21], v[14:15], v[20:21]
	s_waitcnt vmcnt(2)
	v_pk_add_f32 v[26:27], v[12:13], v[26:27]
	v_pk_add_f32 v[24:25], v[10:11], v[24:25]
	v_cvt_pk_bf16_f32 v10, v20, v21
	v_cvt_pk_bf16_f32 v11, v22, v23
	v_cvt_pk_bf16_f32 v12, v24, v25
	v_cvt_pk_bf16_f32 v13, v26, v27
	v_pk_mul_f32 v[14:15], v[80:81], v[22:23]
	v_pk_mul_f32 v[16:17], v[78:79], v[20:21]
	v_pk_mul_f32 v[34:35], v[76:77], v[26:27]
	v_pk_mul_f32 v[36:37], v[74:75], v[24:25]
	global_store_dwordx4 v[30:31], v[10:13], off
	v_mul_f32_e32 v21, v21, v21
	v_mul_f32_e32 v23, v23, v23
	v_cvt_pk_bf16_f32 v10, v16, v17
	v_cvt_pk_bf16_f32 v11, v14, v15
	v_cvt_pk_bf16_f32 v12, v36, v37
	v_cvt_pk_bf16_f32 v13, v34, v35
	global_store_dwordx4 v[32:33], v[10:13], off
	s_nop 0
	s_nop 0
	s_nop 0
	v_mul_f32_e32 v25, v25, v25
	v_mul_f32_e32 v27, v27, v27
	v_fmac_f32_e32 v21, v20, v20
	v_fmac_f32_e32 v23, v22, v22
	v_fmac_f32_e32 v25, v24, v24
	v_fmac_f32_e32 v27, v26, v26
	v_add_f32_e32 v20, v21, v23
	v_add_f32_e32 v21, v25, v27
	v_add_f32_e32 v20, v20, v21
	s_waitcnt vmcnt(3)
	v_pk_add_f32 v[8:9], v[8:9], v[206:207]
	v_pk_add_f32 v[6:7], v[6:7], v[204:205]
	s_waitcnt vmcnt(2)
	v_pk_add_f32 v[10:11], v[4:5], v[210:211]
	v_pk_add_f32 v[12:13], v[2:3], v[208:209]
	v_mul_f32_e32 v16, v7, v7
	v_mul_f32_e32 v17, v9, v9
	v_mul_f32_e32 v21, v13, v13
	v_mul_f32_e32 v22, v11, v11
	v_cvt_pk_bf16_f32 v2, v6, v7
	v_cvt_pk_bf16_f32 v3, v8, v9
	v_cvt_pk_bf16_f32 v4, v12, v13
	v_cvt_pk_bf16_f32 v5, v10, v11
	v_fmac_f32_e32 v16, v6, v6
	v_fmac_f32_e32 v17, v8, v8
	v_fmac_f32_e32 v21, v12, v12
	v_fmac_f32_e32 v22, v10, v10
	global_store_dwordx4 v[30:31], v[2:5], off offset:256
	v_pk_mul_f32 v[14:15], v[72:73], v[8:9]
	v_pk_mul_f32 v[8:9], v[60:61], v[10:11]
	v_add_f32_e32 v2, v16, v17
	v_add_f32_e32 v3, v21, v22
	v_add_f32_e32 v2, v2, v3
	v_add_f32_e32 v16, v20, v2
	ds_bpermute_b32 v17, v139, v16
	v_pk_mul_f32 v[2:3], v[70:71], v[6:7]
	v_pk_mul_f32 v[6:7], v[58:59], v[12:13]
	v_cvt_pk_bf16_f32 v4, v2, v3
	v_cvt_pk_bf16_f32 v5, v14, v15
	s_waitcnt lgkmcnt(0)
	v_add_f32_e32 v2, v16, v17
	ds_bpermute_b32 v3, v138, v2
	v_cvt_pk_bf16_f32 v6, v6, v7
	v_cvt_pk_bf16_f32 v7, v8, v9
	v_lshl_add_u64 v[8:9], v[50:51], 0, v[154:155]
	global_store_dwordx4 v[8:9], v[4:7], off
	s_and_saveexec_b64 s[38:39], s[4:5]
	s_cbranch_execz .LBB0_546
	v_lshl_add_u64 v[4:5], v[18:19], 2, s[20:21]
	s_waitcnt lgkmcnt(0)
	v_add_f32_e32 v2, v2, v3
	global_atomic_add_f32 v[4:5], v2, off
